# v017 plus accumulator zeroing with v_mov_b64 pairs (63 fewer VALU per GEMM unit), instruction selection
# speedup vs baseline: 1.0074x; 1.0037x over previous
; template <class Epi>
; __device__ __forceinline__ void gemm_phase(LAS unsigned char* lds, const GSched& S, const int K, const int lda, const int ldb, const Epi& E) {
;     ...
; #pragma unroll
;         for (int a = 0; a < 2; ++a)
; #pragma unroll
;             for (int b = 0; b < 2; ++b)
; #pragma unroll
;                 for (int m = 0; m < 4; ++m)
; #pragma unroll
;                     for (int n = 0; n < 2; ++n) acc[a][b][m][n] = (f32x4){0.f, 0.f, 0.f, 0.f};
.LBB0_261:
	s_add_u32 s59, s28, 0x100
	v_mov_b32_e32 v0, 0
	s_addc_u32 s60, s29, 0
	s_mov_b32 s61, -2
	v_mov_b64_e32 v[0:1], 0
	v_mov_b64_e32 v[2:3], 0
	v_mov_b64_e32 v[4:5], 0
	v_mov_b64_e32 v[6:7], 0
	v_mov_b64_e32 v[8:9], 0
	v_mov_b64_e32 v[10:11], 0
	v_mov_b64_e32 v[12:13], 0
	v_mov_b64_e32 v[14:15], 0
	v_mov_b64_e32 v[16:17], 0
	v_mov_b64_e32 v[18:19], 0
	v_mov_b64_e32 v[20:21], 0
	v_mov_b64_e32 v[22:23], 0
	v_mov_b64_e32 v[24:25], 0
	v_mov_b64_e32 v[26:27], 0
	v_mov_b64_e32 v[28:29], 0
	v_mov_b64_e32 v[30:31], 0
	v_mov_b64_e32 v[32:33], 0
	v_mov_b64_e32 v[34:35], 0
	v_mov_b64_e32 v[36:37], 0
	v_mov_b64_e32 v[38:39], 0
	v_mov_b64_e32 v[40:41], 0
	v_mov_b64_e32 v[42:43], 0
	v_mov_b64_e32 v[44:45], 0
	v_mov_b64_e32 v[46:47], 0
	v_mov_b64_e32 v[48:49], 0
	v_mov_b64_e32 v[50:51], 0
	v_mov_b64_e32 v[52:53], 0
	v_mov_b64_e32 v[54:55], 0
	v_mov_b64_e32 v[56:57], 0
	v_mov_b64_e32 v[58:59], 0
	v_mov_b64_e32 v[60:61], 0
	v_mov_b64_e32 v[62:63], 0
	v_mov_b64_e32 v[64:65], 0
	v_mov_b64_e32 v[66:67], 0
	v_mov_b64_e32 v[68:69], 0
	v_mov_b64_e32 v[70:71], 0
	v_mov_b64_e32 v[72:73], 0
	v_mov_b64_e32 v[74:75], 0
	v_mov_b64_e32 v[76:77], 0
	v_mov_b64_e32 v[78:79], 0
	v_mov_b64_e32 v[80:81], 0
	v_mov_b64_e32 v[82:83], 0
	v_mov_b64_e32 v[84:85], 0
	v_mov_b64_e32 v[86:87], 0
	v_mov_b64_e32 v[88:89], 0
	v_mov_b64_e32 v[90:91], 0
	v_mov_b64_e32 v[92:93], 0
	v_mov_b64_e32 v[94:95], 0
	v_mov_b64_e32 v[96:97], 0
	v_mov_b64_e32 v[98:99], 0
	v_mov_b64_e32 v[100:101], 0
	v_mov_b64_e32 v[102:103], 0
	v_mov_b64_e32 v[104:105], 0
	v_mov_b64_e32 v[106:107], 0
	v_mov_b64_e32 v[108:109], 0
	v_mov_b64_e32 v[110:111], 0
	v_mov_b64_e32 v[112:113], 0
	v_mov_b64_e32 v[114:115], 0
	v_mov_b64_e32 v[116:117], 0
	v_mov_b64_e32 v[118:119], 0
	v_mov_b64_e32 v[120:121], 0
	v_mov_b64_e32 v[122:123], 0
	v_mov_b64_e32 v[124:125], 0
	v_mov_b64_e32 v[126:127], 0
	s_nop 0

; template <class Epi>
; __device__ __forceinline__ void gemm_phase(LAS unsigned char* lds, const GSched& S, const int K, const int lda, const int ldb, const Epi& E) {
;     ...
; #pragma unroll
;         for (int a = 0; a < 2; ++a)
; #pragma unroll
;             for (int b = 0; b < 2; ++b)
; #pragma unroll
;                 for (int m = 0; m < 4; ++m)
; #pragma unroll
;                     for (int n = 0; n < 2; ++n) acc[a][b][m][n] = (f32x4){0.f, 0.f, 0.f, 0.f};
.LBB0_342:
	s_add_u32 s52, s26, 0x100
	v_mov_b32_e32 v0, 0
	s_addc_u32 s53, s27, 0
	s_mov_b32 s54, -2
	s_waitcnt lgkmcnt(0)
	v_mov_b64_e32 v[0:1], 0
	v_mov_b64_e32 v[2:3], 0
	v_mov_b64_e32 v[4:5], 0
	v_mov_b64_e32 v[6:7], 0
	v_mov_b64_e32 v[8:9], 0
	v_mov_b64_e32 v[10:11], 0
	v_mov_b64_e32 v[12:13], 0
	v_mov_b64_e32 v[14:15], 0
	v_mov_b64_e32 v[16:17], 0
	v_mov_b64_e32 v[18:19], 0
	v_mov_b64_e32 v[20:21], 0
	v_mov_b64_e32 v[22:23], 0
	v_mov_b64_e32 v[24:25], 0
	v_mov_b64_e32 v[26:27], 0
	v_mov_b64_e32 v[28:29], 0
	v_mov_b64_e32 v[30:31], 0
	v_mov_b64_e32 v[32:33], 0
	v_mov_b64_e32 v[34:35], 0
	v_mov_b64_e32 v[36:37], 0
	v_mov_b64_e32 v[38:39], 0
	v_mov_b64_e32 v[40:41], 0
	v_mov_b64_e32 v[42:43], 0
	v_mov_b64_e32 v[44:45], 0
	v_mov_b64_e32 v[46:47], 0
	v_mov_b64_e32 v[48:49], 0
	v_mov_b64_e32 v[50:51], 0
	v_mov_b64_e32 v[52:53], 0
	v_mov_b64_e32 v[54:55], 0
	v_mov_b64_e32 v[56:57], 0
	v_mov_b64_e32 v[58:59], 0
	v_mov_b64_e32 v[60:61], 0
	v_mov_b64_e32 v[62:63], 0
	v_mov_b64_e32 v[64:65], 0
	v_mov_b64_e32 v[66:67], 0
	v_mov_b64_e32 v[68:69], 0
	v_mov_b64_e32 v[70:71], 0
	v_mov_b64_e32 v[72:73], 0
	v_mov_b64_e32 v[74:75], 0
	v_mov_b64_e32 v[76:77], 0
	v_mov_b64_e32 v[78:79], 0
	v_mov_b64_e32 v[80:81], 0
	v_mov_b64_e32 v[82:83], 0
	v_mov_b64_e32 v[84:85], 0
	v_mov_b64_e32 v[86:87], 0
	v_mov_b64_e32 v[88:89], 0
	v_mov_b64_e32 v[90:91], 0
	v_mov_b64_e32 v[92:93], 0
	v_mov_b64_e32 v[94:95], 0
	v_mov_b64_e32 v[96:97], 0
	v_mov_b64_e32 v[98:99], 0
	v_mov_b64_e32 v[100:101], 0
	v_mov_b64_e32 v[102:103], 0
	v_mov_b64_e32 v[104:105], 0
	v_mov_b64_e32 v[106:107], 0
	v_mov_b64_e32 v[108:109], 0
	v_mov_b64_e32 v[110:111], 0
	v_mov_b64_e32 v[112:113], 0
	v_mov_b64_e32 v[114:115], 0
	v_mov_b64_e32 v[116:117], 0
	v_mov_b64_e32 v[118:119], 0
	v_mov_b64_e32 v[120:121], 0
	v_mov_b64_e32 v[122:123], 0
	v_mov_b64_e32 v[124:125], 0
	v_mov_b64_e32 v[126:127], 0
	s_nop 0

; template <class Epi>
; __device__ __forceinline__ void gemm_phase(LAS unsigned char* lds, const GSched& S, const int K, const int lda, const int ldb, const Epi& E) {
;     ...
; #pragma unroll
;         for (int a = 0; a < 2; ++a)
; #pragma unroll
;             for (int b = 0; b < 2; ++b)
; #pragma unroll
;                 for (int m = 0; m < 4; ++m)
; #pragma unroll
;                     for (int n = 0; n < 2; ++n) acc[a][b][m][n] = (f32x4){0.f, 0.f, 0.f, 0.f};
.LBB0_437:
	s_add_u32 s46, s6, 0x100
	v_mov_b32_e32 v0, 0
	s_addc_u32 s47, s7, 0
	s_mov_b32 s48, -2
	s_waitcnt lgkmcnt(0)
	v_mov_b64_e32 v[0:1], 0
	v_mov_b64_e32 v[2:3], 0
	v_mov_b64_e32 v[4:5], 0
	v_mov_b64_e32 v[6:7], 0
	v_mov_b64_e32 v[8:9], 0
	v_mov_b64_e32 v[10:11], 0
	v_mov_b64_e32 v[12:13], 0
	v_mov_b64_e32 v[14:15], 0
	v_mov_b64_e32 v[16:17], 0
	v_mov_b64_e32 v[18:19], 0
	v_mov_b64_e32 v[20:21], 0
	v_mov_b64_e32 v[22:23], 0
	v_mov_b64_e32 v[24:25], 0
	v_mov_b64_e32 v[26:27], 0
	v_mov_b64_e32 v[28:29], 0
	v_mov_b64_e32 v[30:31], 0
	v_mov_b64_e32 v[32:33], 0
	v_mov_b64_e32 v[34:35], 0
	v_mov_b64_e32 v[36:37], 0
	v_mov_b64_e32 v[38:39], 0
	v_mov_b64_e32 v[40:41], 0
	v_mov_b64_e32 v[42:43], 0
	v_mov_b64_e32 v[44:45], 0
	v_mov_b64_e32 v[46:47], 0
	v_mov_b64_e32 v[48:49], 0
	v_mov_b64_e32 v[50:51], 0
	v_mov_b64_e32 v[52:53], 0
	v_mov_b64_e32 v[54:55], 0
	v_mov_b64_e32 v[56:57], 0
	v_mov_b64_e32 v[58:59], 0
	v_mov_b64_e32 v[60:61], 0
	v_mov_b64_e32 v[62:63], 0
	v_mov_b64_e32 v[64:65], 0
	v_mov_b64_e32 v[66:67], 0
	v_mov_b64_e32 v[68:69], 0
	v_mov_b64_e32 v[70:71], 0
	v_mov_b64_e32 v[72:73], 0
	v_mov_b64_e32 v[74:75], 0
	v_mov_b64_e32 v[76:77], 0
	v_mov_b64_e32 v[78:79], 0
	v_mov_b64_e32 v[80:81], 0
	v_mov_b64_e32 v[82:83], 0
	v_mov_b64_e32 v[84:85], 0
	v_mov_b64_e32 v[86:87], 0
	v_mov_b64_e32 v[88:89], 0
	v_mov_b64_e32 v[90:91], 0
	v_mov_b64_e32 v[92:93], 0
	v_mov_b64_e32 v[94:95], 0
	v_mov_b64_e32 v[96:97], 0
	v_mov_b64_e32 v[98:99], 0
	v_mov_b64_e32 v[100:101], 0
	v_mov_b64_e32 v[102:103], 0
	v_mov_b64_e32 v[104:105], 0
	v_mov_b64_e32 v[106:107], 0
	v_mov_b64_e32 v[108:109], 0
	v_mov_b64_e32 v[110:111], 0
	v_mov_b64_e32 v[112:113], 0
	v_mov_b64_e32 v[114:115], 0
	v_mov_b64_e32 v[116:117], 0
	v_mov_b64_e32 v[118:119], 0
	v_mov_b64_e32 v[120:121], 0
	v_mov_b64_e32 v[122:123], 0
	v_mov_b64_e32 v[124:125], 0
	v_mov_b64_e32 v[126:127], 0
	s_nop 0

; template <class Epi>
; __device__ __forceinline__ void gemm_phase(LAS unsigned char* lds, const GSched& S, const int K, const int lda, const int ldb, const Epi& E) {
;     ...
;         const char* nA = has_next ? (nxt.z ? S.A1 : S.A0) + (size_t)nxt.pm * tstepA : cA; const char* nB = has_next ? (nxt.z ? S.B1 : S.B0) + (size_t)nxt.pn * tstepB : cB;
;     ...
; #pragma unroll
;         for (int a = 0; a < 2; ++a)
; #pragma unroll
;             for (int b = 0; b < 2; ++b)
; #pragma unroll
;                 for (int m = 0; m < 4; ++m)
; #pragma unroll
;                     for (int n = 0; n < 2; ++n) acc[a][b][m][n] = (f32x4){0.f, 0.f, 0.f, 0.f};
.LBB0_542:
	s_ashr_i32 s45, s44, 31
	s_lshl_b64 s[2:3], s[44:45], 19
	s_cmp_eq_u32 s78, 0
	s_cselect_b32 s4, s53, s55
	s_cselect_b32 s1, s54, s56
	s_cselect_b32 s10, s13, s58
	s_cselect_b32 s11, s12, s57
	s_add_u32 s46, s4, s2
	s_addc_u32 s47, s1, s3
	s_and_b64 s[2:3], s[50:51], exec
	s_cselect_b32 s1, s47, s9
	s_cselect_b32 s2, s46, s8
	s_ashr_i32 s43, s42, 31
	s_lshl_b64 s[4:5], s[42:43], 18
	s_add_u32 s48, s11, s4
	s_addc_u32 s49, s10, s5
	s_and_b64 s[4:5], s[50:51], exec
	s_cselect_b32 s4, s49, s7
	s_cselect_b32 s5, s48, s6
	s_add_u32 s43, s6, 0x100
	s_addc_u32 s45, s7, 0
	s_add_u32 s6, s8, 0x40080
	v_mov_b32_e32 v0, 0
	s_addc_u32 s7, s9, 0
	s_mov_b32 s77, -2
	v_mov_b64_e32 v[0:1], 0
	v_mov_b64_e32 v[2:3], 0
	v_mov_b64_e32 v[4:5], 0
	v_mov_b64_e32 v[6:7], 0
	v_mov_b64_e32 v[8:9], 0
	v_mov_b64_e32 v[10:11], 0
	v_mov_b64_e32 v[12:13], 0
	v_mov_b64_e32 v[14:15], 0
	v_mov_b64_e32 v[16:17], 0
	v_mov_b64_e32 v[18:19], 0
	v_mov_b64_e32 v[20:21], 0
	v_mov_b64_e32 v[22:23], 0
	v_mov_b64_e32 v[24:25], 0
	v_mov_b64_e32 v[26:27], 0
	v_mov_b64_e32 v[28:29], 0
	v_mov_b64_e32 v[30:31], 0
	v_mov_b64_e32 v[32:33], 0
	v_mov_b64_e32 v[34:35], 0
	v_mov_b64_e32 v[36:37], 0
	v_mov_b64_e32 v[38:39], 0
	v_mov_b64_e32 v[40:41], 0
	v_mov_b64_e32 v[42:43], 0
	v_mov_b64_e32 v[44:45], 0
	v_mov_b64_e32 v[46:47], 0
	v_mov_b64_e32 v[48:49], 0
	v_mov_b64_e32 v[50:51], 0
	v_mov_b64_e32 v[52:53], 0
	v_mov_b64_e32 v[54:55], 0
	v_mov_b64_e32 v[56:57], 0
	v_mov_b64_e32 v[58:59], 0
	v_mov_b64_e32 v[60:61], 0
	v_mov_b64_e32 v[62:63], 0
	v_mov_b64_e32 v[64:65], 0
	v_mov_b64_e32 v[66:67], 0
	v_mov_b64_e32 v[68:69], 0
	v_mov_b64_e32 v[70:71], 0
	v_mov_b64_e32 v[72:73], 0
	v_mov_b64_e32 v[74:75], 0
	v_mov_b64_e32 v[76:77], 0
	v_mov_b64_e32 v[78:79], 0
	v_mov_b64_e32 v[80:81], 0
	v_mov_b64_e32 v[82:83], 0
	v_mov_b64_e32 v[84:85], 0
	v_mov_b64_e32 v[86:87], 0
	v_mov_b64_e32 v[88:89], 0
	v_mov_b64_e32 v[90:91], 0
	v_mov_b64_e32 v[92:93], 0
	v_mov_b64_e32 v[94:95], 0
	v_mov_b64_e32 v[96:97], 0
	v_mov_b64_e32 v[98:99], 0
	v_mov_b64_e32 v[100:101], 0
	v_mov_b64_e32 v[102:103], 0
	v_mov_b64_e32 v[104:105], 0
	v_mov_b64_e32 v[106:107], 0
	v_mov_b64_e32 v[108:109], 0
	v_mov_b64_e32 v[110:111], 0
	v_mov_b64_e32 v[112:113], 0
	v_mov_b64_e32 v[114:115], 0
	v_mov_b64_e32 v[116:117], 0
	v_mov_b64_e32 v[118:119], 0
	v_mov_b64_e32 v[120:121], 0
	v_mov_b64_e32 v[122:123], 0
	v_mov_b64_e32 v[124:125], 0
	v_mov_b64_e32 v[126:127], 0
	s_nop 0

; template <class Epi>
; __device__ __forceinline__ void gemm_phase(LAS unsigned char* lds, const GSched& S, const int K, const int lda, const int ldb, const Epi& E) {
;     ...
; #pragma unroll
;         for (int a = 0; a < 2; ++a)
; #pragma unroll
;             for (int b = 0; b < 2; ++b)
; #pragma unroll
;                 for (int m = 0; m < 4; ++m)
; #pragma unroll
;                     for (int n = 0; n < 2; ++n) acc[a][b][m][n] = (f32x4){0.f, 0.f, 0.f, 0.f};
.LBB0_768:
	s_add_u32 s4, s34, 0x100
	v_mov_b32_e32 v0, 0
	s_addc_u32 s5, s35, 0
	s_mov_b32 s64, -2
	v_mov_b64_e32 v[0:1], 0
	v_mov_b64_e32 v[2:3], 0
	v_mov_b64_e32 v[4:5], 0
	v_mov_b64_e32 v[6:7], 0
	v_mov_b64_e32 v[8:9], 0
	v_mov_b64_e32 v[10:11], 0
	v_mov_b64_e32 v[12:13], 0
	v_mov_b64_e32 v[14:15], 0
	v_mov_b64_e32 v[16:17], 0
	v_mov_b64_e32 v[18:19], 0
	v_mov_b64_e32 v[20:21], 0
	v_mov_b64_e32 v[22:23], 0
	v_mov_b64_e32 v[24:25], 0
	v_mov_b64_e32 v[26:27], 0
	v_mov_b64_e32 v[28:29], 0
	v_mov_b64_e32 v[30:31], 0
	v_mov_b64_e32 v[32:33], 0
	v_mov_b64_e32 v[34:35], 0
	v_mov_b64_e32 v[36:37], 0
	v_mov_b64_e32 v[38:39], 0
	v_mov_b64_e32 v[40:41], 0
	v_mov_b64_e32 v[42:43], 0
	v_mov_b64_e32 v[44:45], 0
	v_mov_b64_e32 v[46:47], 0
	v_mov_b64_e32 v[48:49], 0
	v_mov_b64_e32 v[50:51], 0
	v_mov_b64_e32 v[52:53], 0
	v_mov_b64_e32 v[54:55], 0
	v_mov_b64_e32 v[56:57], 0
	v_mov_b64_e32 v[58:59], 0
	v_mov_b64_e32 v[60:61], 0
	v_mov_b64_e32 v[62:63], 0
	v_mov_b64_e32 v[64:65], 0
	v_mov_b64_e32 v[66:67], 0
	v_mov_b64_e32 v[68:69], 0
	v_mov_b64_e32 v[70:71], 0
	v_mov_b64_e32 v[72:73], 0
	v_mov_b64_e32 v[74:75], 0
	v_mov_b64_e32 v[76:77], 0
	v_mov_b64_e32 v[78:79], 0
	v_mov_b64_e32 v[80:81], 0
	v_mov_b64_e32 v[82:83], 0
	v_mov_b64_e32 v[84:85], 0
	v_mov_b64_e32 v[86:87], 0
	v_mov_b64_e32 v[88:89], 0
	v_mov_b64_e32 v[90:91], 0
	v_mov_b64_e32 v[92:93], 0
	v_mov_b64_e32 v[94:95], 0
	v_mov_b64_e32 v[96:97], 0
	v_mov_b64_e32 v[98:99], 0
	v_mov_b64_e32 v[100:101], 0
	v_mov_b64_e32 v[102:103], 0
	v_mov_b64_e32 v[104:105], 0
	v_mov_b64_e32 v[106:107], 0
	v_mov_b64_e32 v[108:109], 0
	v_mov_b64_e32 v[110:111], 0
	v_mov_b64_e32 v[112:113], 0
	v_mov_b64_e32 v[114:115], 0
	v_mov_b64_e32 v[116:117], 0
	v_mov_b64_e32 v[118:119], 0
	v_mov_b64_e32 v[120:121], 0
	v_mov_b64_e32 v[122:123], 0
	v_mov_b64_e32 v[124:125], 0
	v_mov_b64_e32 v[126:127], 0
	s_nop 0

; template <class Epi>
; __device__ __forceinline__ void gemm_phase(LAS unsigned char* lds, const GSched& S, const int K, const int lda, const int ldb, const Epi& E) {
;     ...
; #pragma unroll
;         for (int a = 0; a < 2; ++a)
; #pragma unroll
;             for (int b = 0; b < 2; ++b)
; #pragma unroll
;                 for (int m = 0; m < 4; ++m)
; #pragma unroll
;                     for (int n = 0; n < 2; ++n) acc[a][b][m][n] = (f32x4){0.f, 0.f, 0.f, 0.f};
.LBB0_861:
	s_ashr_i32 s19, s18, 31
	s_lshl_b64 s[0:1], s[18:19], 20
	s_add_u32 s22, s31, s0
	s_addc_u32 s23, s33, s1
	s_and_b64 s[0:1], s[8:9], exec
	s_cselect_b32 s0, s23, s29
	s_cselect_b32 s1, s22, s28
	s_lshl_b32 s8, s2, 8
	s_ashr_i32 s9, s8, 31
	s_add_u32 s2, s26, 0x100
	s_addc_u32 s4, s27, 0
	s_add_u32 s5, s28, 0x100
	v_mov_b32_e32 v0, 0
	v_lshl_add_u32 v190, s24, 8, v204
	v_lshl_add_u64 v[140:141], s[8:9], 1, v[180:181]
	v_lshl_add_u64 v[142:143], s[28:29], 0, v[182:183]
	v_lshl_add_u64 v[144:145], s[28:29], 0, v[184:185]
	s_addc_u32 s9, s29, 0
	s_mov_b32 s19, 0
	s_mov_b64 s[24:25], 0
	v_mov_b64_e32 v[0:1], 0
	v_mov_b64_e32 v[2:3], 0
	v_mov_b64_e32 v[4:5], 0
	v_mov_b64_e32 v[6:7], 0
	v_mov_b64_e32 v[8:9], 0
	v_mov_b64_e32 v[10:11], 0
	v_mov_b64_e32 v[12:13], 0
	v_mov_b64_e32 v[14:15], 0
	v_mov_b64_e32 v[16:17], 0
	v_mov_b64_e32 v[18:19], 0
	v_mov_b64_e32 v[20:21], 0
	v_mov_b64_e32 v[22:23], 0
	v_mov_b64_e32 v[24:25], 0
	v_mov_b64_e32 v[26:27], 0
	v_mov_b64_e32 v[28:29], 0
	v_mov_b64_e32 v[30:31], 0
	v_mov_b64_e32 v[32:33], 0
	v_mov_b64_e32 v[34:35], 0
	v_mov_b64_e32 v[36:37], 0
	v_mov_b64_e32 v[38:39], 0
	v_mov_b64_e32 v[40:41], 0
	v_mov_b64_e32 v[42:43], 0
	v_mov_b64_e32 v[44:45], 0
	v_mov_b64_e32 v[46:47], 0
	v_mov_b64_e32 v[48:49], 0
	v_mov_b64_e32 v[50:51], 0
	v_mov_b64_e32 v[52:53], 0
	v_mov_b64_e32 v[54:55], 0
	v_mov_b64_e32 v[56:57], 0
	v_mov_b64_e32 v[58:59], 0
	v_mov_b64_e32 v[60:61], 0
	v_mov_b64_e32 v[62:63], 0
	v_mov_b64_e32 v[64:65], 0
	v_mov_b64_e32 v[66:67], 0
	v_mov_b64_e32 v[68:69], 0
	v_mov_b64_e32 v[70:71], 0
	v_mov_b64_e32 v[72:73], 0
	v_mov_b64_e32 v[74:75], 0
	v_mov_b64_e32 v[76:77], 0
	v_mov_b64_e32 v[78:79], 0
	v_mov_b64_e32 v[80:81], 0
	v_mov_b64_e32 v[82:83], 0
	v_mov_b64_e32 v[84:85], 0
	v_mov_b64_e32 v[86:87], 0
	v_mov_b64_e32 v[88:89], 0
	v_mov_b64_e32 v[90:91], 0
	v_mov_b64_e32 v[92:93], 0
	v_mov_b64_e32 v[94:95], 0
	v_mov_b64_e32 v[96:97], 0
	v_mov_b64_e32 v[98:99], 0
	v_mov_b64_e32 v[100:101], 0
	v_mov_b64_e32 v[102:103], 0
	v_mov_b64_e32 v[104:105], 0
	v_mov_b64_e32 v[106:107], 0
	v_mov_b64_e32 v[108:109], 0
	v_mov_b64_e32 v[110:111], 0
	v_mov_b64_e32 v[112:113], 0
	v_mov_b64_e32 v[114:115], 0
	v_mov_b64_e32 v[116:117], 0
	v_mov_b64_e32 v[118:119], 0
	v_mov_b64_e32 v[120:121], 0
	v_mov_b64_e32 v[122:123], 0
	v_mov_b64_e32 v[124:125], 0
	v_mov_b64_e32 v[126:127], 0
	s_nop 0

; template <class Epi>
; __device__ __forceinline__ void gemm_phase(LAS unsigned char* lds, const GSched& S, const int K, const int lda, const int ldb, const Epi& E) {
;     ...
; #pragma unroll
;         for (int a = 0; a < 2; ++a)
; #pragma unroll
;             for (int b = 0; b < 2; ++b)
; #pragma unroll
;                 for (int m = 0; m < 4; ++m)
; #pragma unroll
;                     for (int n = 0; n < 2; ++n) acc[a][b][m][n] = (f32x4){0.f, 0.f, 0.f, 0.f};
.LBB0_940:
	s_ashr_i32 s21, s20, 31
	s_lshl_b64 s[24:25], s[20:21], 20
	s_add_u32 s24, s30, s24
	s_addc_u32 s25, s31, s25
	s_and_b64 s[10:11], s[10:11], exec
	s_cselect_b32 s21, s25, s29
	s_cselect_b32 s47, s24, s28
	s_add_u32 s48, s26, 0x100
	s_addc_u32 s49, s27, 0
	s_add_u32 s10, s28, 0x80080
	v_mov_b32_e32 v0, 0
	s_addc_u32 s11, s29, 0
	s_mov_b32 s50, -2
	s_waitcnt lgkmcnt(0)
	v_mov_b64_e32 v[0:1], 0
	v_mov_b64_e32 v[2:3], 0
	v_mov_b64_e32 v[4:5], 0
	v_mov_b64_e32 v[6:7], 0
	v_mov_b64_e32 v[8:9], 0
	v_mov_b64_e32 v[10:11], 0
	v_mov_b64_e32 v[12:13], 0
	v_mov_b64_e32 v[14:15], 0
	v_mov_b64_e32 v[16:17], 0
	v_mov_b64_e32 v[18:19], 0
	v_mov_b64_e32 v[20:21], 0
	v_mov_b64_e32 v[22:23], 0
	v_mov_b64_e32 v[24:25], 0
	v_mov_b64_e32 v[26:27], 0
	v_mov_b64_e32 v[28:29], 0
	v_mov_b64_e32 v[30:31], 0
	v_mov_b64_e32 v[32:33], 0
	v_mov_b64_e32 v[34:35], 0
	v_mov_b64_e32 v[36:37], 0
	v_mov_b64_e32 v[38:39], 0
	v_mov_b64_e32 v[40:41], 0
	v_mov_b64_e32 v[42:43], 0
	v_mov_b64_e32 v[44:45], 0
	v_mov_b64_e32 v[46:47], 0
	v_mov_b64_e32 v[48:49], 0
	v_mov_b64_e32 v[50:51], 0
	v_mov_b64_e32 v[52:53], 0
	v_mov_b64_e32 v[54:55], 0
	v_mov_b64_e32 v[56:57], 0
	v_mov_b64_e32 v[58:59], 0
	v_mov_b64_e32 v[60:61], 0
	v_mov_b64_e32 v[62:63], 0
	v_mov_b64_e32 v[64:65], 0
	v_mov_b64_e32 v[66:67], 0
	v_mov_b64_e32 v[68:69], 0
	v_mov_b64_e32 v[70:71], 0
	v_mov_b64_e32 v[72:73], 0
	v_mov_b64_e32 v[74:75], 0
	v_mov_b64_e32 v[76:77], 0
	v_mov_b64_e32 v[78:79], 0
	v_mov_b64_e32 v[80:81], 0
	v_mov_b64_e32 v[82:83], 0
	v_mov_b64_e32 v[84:85], 0
	v_mov_b64_e32 v[86:87], 0
	v_mov_b64_e32 v[88:89], 0
	v_mov_b64_e32 v[90:91], 0
	v_mov_b64_e32 v[92:93], 0
	v_mov_b64_e32 v[94:95], 0
	v_mov_b64_e32 v[96:97], 0
	v_mov_b64_e32 v[98:99], 0
	v_mov_b64_e32 v[100:101], 0
	v_mov_b64_e32 v[102:103], 0
	v_mov_b64_e32 v[108:109], 0
	v_mov_b64_e32 v[110:111], 0
	v_mov_b64_e32 v[112:113], 0
	v_mov_b64_e32 v[114:115], 0
	v_mov_b64_e32 v[120:121], 0
	v_mov_b64_e32 v[122:123], 0
	v_mov_b64_e32 v[124:125], 0
	v_mov_b64_e32 v[126:127], 0
	v_mov_b64_e32 v[132:133], 0
	v_mov_b64_e32 v[134:135], 0
	v_mov_b64_e32 v[136:137], 0
	v_mov_b64_e32 v[138:139], 0
	s_nop 0

; template <class Epi>
; __device__ __forceinline__ void gemm_phase(LAS unsigned char* lds, const GSched& S, const int K, const int lda, const int ldb, const Epi& E) {
;     ...
; #pragma unroll
;         for (int a = 0; a < 2; ++a)
; #pragma unroll
;             for (int b = 0; b < 2; ++b)
; #pragma unroll
;                 for (int m = 0; m < 4; ++m)
; #pragma unroll
;                     for (int n = 0; n < 2; ++n) acc[a][b][m][n] = (f32x4){0.f, 0.f, 0.f, 0.f};
.LBB0_1025:
	s_add_u32 s57, s30, 0x100
	v_mov_b32_e32 v0, 0
	s_addc_u32 s58, s31, 0
	s_mov_b32 s59, -2
	v_mov_b64_e32 v[0:1], 0
	v_mov_b64_e32 v[2:3], 0
	v_mov_b64_e32 v[4:5], 0
	v_mov_b64_e32 v[6:7], 0
	v_mov_b64_e32 v[8:9], 0
	v_mov_b64_e32 v[10:11], 0
	v_mov_b64_e32 v[12:13], 0
	v_mov_b64_e32 v[14:15], 0
	v_mov_b64_e32 v[16:17], 0
	v_mov_b64_e32 v[18:19], 0
	v_mov_b64_e32 v[20:21], 0
	v_mov_b64_e32 v[22:23], 0
	v_mov_b64_e32 v[24:25], 0
	v_mov_b64_e32 v[26:27], 0
	v_mov_b64_e32 v[28:29], 0
	v_mov_b64_e32 v[30:31], 0
	v_mov_b64_e32 v[32:33], 0
	v_mov_b64_e32 v[34:35], 0
	v_mov_b64_e32 v[36:37], 0
	v_mov_b64_e32 v[38:39], 0
	v_mov_b64_e32 v[40:41], 0
	v_mov_b64_e32 v[42:43], 0
	v_mov_b64_e32 v[44:45], 0
	v_mov_b64_e32 v[46:47], 0
	v_mov_b64_e32 v[48:49], 0
	v_mov_b64_e32 v[50:51], 0
	v_mov_b64_e32 v[52:53], 0
	v_mov_b64_e32 v[54:55], 0
	v_mov_b64_e32 v[56:57], 0
	v_mov_b64_e32 v[58:59], 0
	v_mov_b64_e32 v[60:61], 0
	v_mov_b64_e32 v[62:63], 0
	v_mov_b64_e32 v[64:65], 0
	v_mov_b64_e32 v[66:67], 0
	v_mov_b64_e32 v[68:69], 0
	v_mov_b64_e32 v[70:71], 0
	v_mov_b64_e32 v[72:73], 0
	v_mov_b64_e32 v[74:75], 0
	v_mov_b64_e32 v[76:77], 0
	v_mov_b64_e32 v[78:79], 0
	v_mov_b64_e32 v[80:81], 0
	v_mov_b64_e32 v[82:83], 0
	v_mov_b64_e32 v[84:85], 0
	v_mov_b64_e32 v[86:87], 0
	v_mov_b64_e32 v[88:89], 0
	v_mov_b64_e32 v[90:91], 0
	v_mov_b64_e32 v[92:93], 0
	v_mov_b64_e32 v[94:95], 0
	v_mov_b64_e32 v[96:97], 0
	v_mov_b64_e32 v[98:99], 0
	v_mov_b64_e32 v[100:101], 0
	v_mov_b64_e32 v[102:103], 0
	v_mov_b64_e32 v[104:105], 0
	v_mov_b64_e32 v[106:107], 0
	v_mov_b64_e32 v[108:109], 0
	v_mov_b64_e32 v[110:111], 0
	v_mov_b64_e32 v[112:113], 0
	v_mov_b64_e32 v[114:115], 0
	v_mov_b64_e32 v[116:117], 0
	v_mov_b64_e32 v[118:119], 0
	v_mov_b64_e32 v[120:121], 0
	v_mov_b64_e32 v[122:123], 0
	v_mov_b64_e32 v[124:125], 0
	v_mov_b64_e32 v[126:127], 0
	s_nop 0

; template <class Epi>
; __device__ __forceinline__ void gemm_phase(LAS unsigned char* lds, const GSched& S, const int K, const int lda, const int ldb, const Epi& E) {
;     ...
; #pragma unroll
;         for (int a = 0; a < 2; ++a)
; #pragma unroll
;             for (int b = 0; b < 2; ++b)
; #pragma unroll
;                 for (int m = 0; m < 4; ++m)
; #pragma unroll
;                     for (int n = 0; n < 2; ++n) acc[a][b][m][n] = (f32x4){0.f, 0.f, 0.f, 0.f};
.LBB0_1106:
	s_add_u32 s48, s24, 0x100
	v_mov_b32_e32 v0, 0
	s_addc_u32 s49, s25, 0
	s_mov_b32 s50, -2
	s_waitcnt lgkmcnt(0)
	v_mov_b64_e32 v[0:1], 0
	v_mov_b64_e32 v[2:3], 0
	v_mov_b64_e32 v[4:5], 0
	v_mov_b64_e32 v[6:7], 0
	v_mov_b64_e32 v[8:9], 0
	v_mov_b64_e32 v[10:11], 0
	v_mov_b64_e32 v[12:13], 0
	v_mov_b64_e32 v[14:15], 0
	v_mov_b64_e32 v[16:17], 0
	v_mov_b64_e32 v[18:19], 0
	v_mov_b64_e32 v[20:21], 0
	v_mov_b64_e32 v[22:23], 0
	v_mov_b64_e32 v[24:25], 0
	v_mov_b64_e32 v[26:27], 0
	v_mov_b64_e32 v[28:29], 0
	v_mov_b64_e32 v[30:31], 0
	v_mov_b64_e32 v[32:33], 0
	v_mov_b64_e32 v[34:35], 0
	v_mov_b64_e32 v[36:37], 0
	v_mov_b64_e32 v[38:39], 0
	v_mov_b64_e32 v[40:41], 0
	v_mov_b64_e32 v[42:43], 0
	v_mov_b64_e32 v[44:45], 0
	v_mov_b64_e32 v[46:47], 0
	v_mov_b64_e32 v[48:49], 0
	v_mov_b64_e32 v[50:51], 0
	v_mov_b64_e32 v[52:53], 0
	v_mov_b64_e32 v[54:55], 0
	v_mov_b64_e32 v[56:57], 0
	v_mov_b64_e32 v[58:59], 0
	v_mov_b64_e32 v[60:61], 0
	v_mov_b64_e32 v[62:63], 0
	v_mov_b64_e32 v[64:65], 0
	v_mov_b64_e32 v[66:67], 0
	v_mov_b64_e32 v[68:69], 0
	v_mov_b64_e32 v[70:71], 0
	v_mov_b64_e32 v[72:73], 0
	v_mov_b64_e32 v[74:75], 0
	v_mov_b64_e32 v[76:77], 0
	v_mov_b64_e32 v[78:79], 0
	v_mov_b64_e32 v[80:81], 0
	v_mov_b64_e32 v[82:83], 0
	v_mov_b64_e32 v[84:85], 0
	v_mov_b64_e32 v[86:87], 0
	v_mov_b64_e32 v[88:89], 0
	v_mov_b64_e32 v[90:91], 0
	v_mov_b64_e32 v[92:93], 0
	v_mov_b64_e32 v[94:95], 0
	v_mov_b64_e32 v[96:97], 0
	v_mov_b64_e32 v[98:99], 0
	v_mov_b64_e32 v[100:101], 0
	v_mov_b64_e32 v[102:103], 0
	v_mov_b64_e32 v[108:109], 0
	v_mov_b64_e32 v[110:111], 0
	v_mov_b64_e32 v[112:113], 0
	v_mov_b64_e32 v[114:115], 0
	v_mov_b64_e32 v[120:121], 0
	v_mov_b64_e32 v[122:123], 0
	v_mov_b64_e32 v[124:125], 0
	v_mov_b64_e32 v[126:127], 0
	v_mov_b64_e32 v[132:133], 0
	v_mov_b64_e32 v[134:135], 0
	v_mov_b64_e32 v[136:137], 0
	v_mov_b64_e32 v[138:139], 0
	s_nop 0

; #define PG8_STAGE(bufoff, gbase, voff) do { _Pragma("unroll") for (int _i = 0; _i < 2; ++_i) \
;         __builtin_amdgcn_global_load_lds((const unsigned*)((const char*)(gbase) + (voff)[_i]), (LAS unsigned*)(lds + (bufoff) + ldsw + _i * 8192), 16, 0, 0); } while (0)
; #define PG8_LDA(dst, b, h) do { _Pragma("unroll") for (int m = 0; m < 4; ++m) _Pragma("unroll") for (int k = 0; k < 2; ++k) dst[m][k] = *(const LAS bf16x8*)(lds + PG8_SA(b, h) + aoff + m * 2048 + k * 1024); } while (0)
; #define PG8_LDB(dst, b, h) do { _Pragma("unroll") for (int n = 0; n < 2; ++n) _Pragma("unroll") for (int k = 0; k < 2; ++k) dst[n][k] = *(const LAS bf16x8*)(lds + PG8_SB(b, h) + boff + n * 2048 + k * 1024); } while (0)
; #define PG8_MMA(ai, bj, At, Bt) do { __builtin_amdgcn_s_setprio(1); _Pragma("unroll") for (int m = 0; m < 4; ++m) _Pragma("unroll") for (int n = 0; n < 2; ++n) _Pragma("unroll") for (int k = 0; k < 2; ++k) \
;         acc[ai][bj][m][n] = __builtin_amdgcn_mfma_f32_16x16x32_bf16(Bt[n][k], At[m][k], acc[ai][bj][m][n], 0, 0, 0); __builtin_amdgcn_s_setprio(0); } while (0)
; #define PG8_WAIT_L(n) asm volatile("s_waitcnt lgkmcnt(" #n ")" ::: "memory")
; #define PG8_BAR __builtin_amdgcn_s_barrier()
; #define PG8_SCHED __builtin_amdgcn_sched_barrier(0)
; template <class Epi>
; __device__ __forceinline__ void gemm_phase(LAS unsigned char* lds, const GSched& S, const int K, const int lda, const int ldb, const Epi& E) {
;     ...
;             PG8_LDB(B0, 0, 0); PG8_SCHED; PG8_LDA(At, 0, 0); PG8_STAGE(PG8_SA(1, 1), a1 + hstepA, voffA);
;             PG8_WAIT_L(8); PG8_BAR; PG8_WAIT_L(0); PG8_MMA(0, 0, At, B0); PG8_BAR; PG8_SCHED;
;             if constexpr (!Epi::NARROW) PG8_LDB(B1, 0, 1); PG8_STAGE(PG8_SB(0, 0), b2, voffB);
;             PG8_BAR; PG8_WAIT_L(0); if constexpr (!Epi::NARROW) PG8_MMA(0, 1, At, B1); PG8_BAR;
;     ...
; #pragma unroll
;         for (int a = 0; a < 2; ++a)
; #pragma unroll
;             for (int b = 0; b < 2; ++b)
; #pragma unroll
;                 for (int m = 0; m < 4; ++m)
; #pragma unroll
;                     for (int n = 0; n < 2; ++n) acc[a][b][m][n] = (f32x4){0.f, 0.f, 0.f, 0.f};
.LBB0_1201:
	s_lshl_b32 s38, s56, 8
	s_ashr_i32 s39, s38, 31
	s_add_u32 s0, s40, 0x100
	s_addc_u32 s1, s41, 0
	s_add_u32 s2, s42, 0x100
	v_mov_b32_e32 v0, 0
	v_lshl_add_u32 v214, s55, 8, v237
	v_lshl_add_u64 v[120:121], s[38:39], 1, v[200:201]
	v_lshl_add_u64 v[122:123], s[42:43], 0, v[204:205]
	v_lshl_add_u64 v[124:125], s[42:43], 0, v[206:207]
	s_addc_u32 s24, s43, 0
	s_mov_b32 s39, 0
	s_mov_b64 s[40:41], 0
	s_waitcnt lgkmcnt(0)
	v_mov_b64_e32 v[0:1], 0
	v_mov_b64_e32 v[2:3], 0
	v_mov_b64_e32 v[4:5], 0
	v_mov_b64_e32 v[6:7], 0
	v_mov_b64_e32 v[8:9], 0
	v_mov_b64_e32 v[10:11], 0
	v_mov_b64_e32 v[12:13], 0
	v_mov_b64_e32 v[14:15], 0
	v_mov_b64_e32 v[16:17], 0
	v_mov_b64_e32 v[18:19], 0
	v_mov_b64_e32 v[20:21], 0
	v_mov_b64_e32 v[22:23], 0
	v_mov_b64_e32 v[24:25], 0
	v_mov_b64_e32 v[26:27], 0
	v_mov_b64_e32 v[28:29], 0
	v_mov_b64_e32 v[30:31], 0
	v_mov_b64_e32 v[32:33], 0
	v_mov_b64_e32 v[34:35], 0
	v_mov_b64_e32 v[36:37], 0
	v_mov_b64_e32 v[38:39], 0
	v_mov_b64_e32 v[40:41], 0
	v_mov_b64_e32 v[42:43], 0
	v_mov_b64_e32 v[44:45], 0
	v_mov_b64_e32 v[46:47], 0
	v_mov_b64_e32 v[48:49], 0
	v_mov_b64_e32 v[50:51], 0
	v_mov_b64_e32 v[52:53], 0
	v_mov_b64_e32 v[54:55], 0
	v_mov_b64_e32 v[56:57], 0
	v_mov_b64_e32 v[58:59], 0
	v_mov_b64_e32 v[60:61], 0
	v_mov_b64_e32 v[62:63], 0
	v_mov_b64_e32 v[64:65], 0
	v_mov_b64_e32 v[66:67], 0
	v_mov_b64_e32 v[68:69], 0
	v_mov_b64_e32 v[70:71], 0
	v_mov_b64_e32 v[72:73], 0
	v_mov_b64_e32 v[74:75], 0
	v_mov_b64_e32 v[76:77], 0
	v_mov_b64_e32 v[78:79], 0
	v_mov_b64_e32 v[80:81], 0
	v_mov_b64_e32 v[82:83], 0
	v_mov_b64_e32 v[84:85], 0
	v_mov_b64_e32 v[86:87], 0
	v_mov_b64_e32 v[88:89], 0
	v_mov_b64_e32 v[90:91], 0
	v_mov_b64_e32 v[92:93], 0
	v_mov_b64_e32 v[94:95], 0
	v_mov_b64_e32 v[96:97], 0
	v_mov_b64_e32 v[98:99], 0
	v_mov_b64_e32 v[100:101], 0
	v_mov_b64_e32 v[102:103], 0
	v_mov_b64_e32 v[104:105], 0
	v_mov_b64_e32 v[106:107], 0
	v_mov_b64_e32 v[108:109], 0
	v_mov_b64_e32 v[110:111], 0
	v_mov_b64_e32 v[112:113], 0
	v_mov_b64_e32 v[114:115], 0
	v_mov_b64_e32 v[116:117], 0
	v_mov_b64_e32 v[118:119], 0
	v_mov_b64_e32 v[128:129], 0
	v_mov_b64_e32 v[130:131], 0
	v_mov_b64_e32 v[148:149], 0
	v_mov_b64_e32 v[150:151], 0
	s_nop 0
.LBB0_1202:
	ds_read_b128 v[132:135], v241
	ds_read_b128 v[136:139], v241 offset:1024
	ds_read_b128 v[140:143], v241 offset:2048
	ds_read_b128 v[144:147], v241 offset:3072
	s_add_u32 s42, s2, s40
	s_addc_u32 s43, s24, s41
	s_add_u32 s75, s0, s40
	s_addc_u32 s76, s1, s41
	s_cmpk_eq_i32 s40, 0x1100
	s_cselect_b32 s44, s36, s42
	s_cselect_b32 s42, s8, s75
	s_cselect_b32 s45, s37, s43
	s_cselect_b32 s43, s9, s76
	v_lshl_add_u64 v[126:127], v[124:125], 0, s[40:41]
	s_add_i32 m0, s48, 0xc000
	ds_read_b128 v[152:155], v240
	ds_read_b128 v[156:159], v240 offset:1024
	ds_read_b128 v[160:163], v240 offset:2048
	ds_read_b128 v[164:167], v240 offset:3072
	ds_read_b128 v[168:171], v240 offset:4096
	ds_read_b128 v[172:175], v240 offset:5120
	ds_read_b128 v[176:179], v240 offset:6144
	ds_read_b128 v[180:183], v240 offset:7168
	global_load_lds_dwordx4 v[126:127], off
	v_lshl_add_u64 v[126:127], v[122:123], 0, s[40:41]
	s_add_i32 m0, s48, 0xe000
	s_nop 0
	global_load_lds_dwordx4 v[126:127], off
	s_waitcnt lgkmcnt(8)
	s_barrier
	s_waitcnt lgkmcnt(0)
	s_setprio 1
	v_mfma_f32_16x16x32_bf16 v[148:151], v[132:135], v[152:155], v[148:151]
	v_mfma_f32_16x16x32_bf16 v[126:129], v[140:143], v[152:155], v[128:131]
	v_mfma_f32_16x16x32_bf16 v[108:111], v[132:135], v[160:163], v[108:111]
	v_mfma_f32_16x16x32_bf16 v[104:107], v[140:143], v[160:163], v[104:107]
	v_mfma_f32_16x16x32_bf16 v[92:95], v[132:135], v[168:171], v[92:95]
	v_mfma_f32_16x16x32_bf16 v[88:91], v[140:143], v[168:171], v[88:91]
	v_mfma_f32_16x16x32_bf16 v[76:79], v[132:135], v[176:179], v[76:79]
	v_mfma_f32_16x16x32_bf16 v[72:75], v[140:143], v[176:179], v[72:75]
	v_mfma_f32_16x16x32_bf16 v[148:151], v[136:139], v[156:159], v[148:151]
	v_mfma_f32_16x16x32_bf16 v[126:129], v[144:147], v[156:159], v[126:129]
	v_mfma_f32_16x16x32_bf16 v[108:111], v[136:139], v[164:167], v[108:111]
	v_mfma_f32_16x16x32_bf16 v[104:107], v[144:147], v[164:167], v[104:107]
	v_mfma_f32_16x16x32_bf16 v[92:95], v[136:139], v[172:175], v[92:95]
	v_mfma_f32_16x16x32_bf16 v[88:91], v[144:147], v[172:175], v[88:91]
	v_mfma_f32_16x16x32_bf16 v[76:79], v[136:139], v[180:183], v[76:79]
	v_mfma_f32_16x16x32_bf16 v[72:75], v[144:147], v[180:183], v[72:75]
	s_setprio 0
	s_barrier
	s_add_i32 s75, s63, s47
	v_lshl_add_u64 v[212:213], s[42:43], 0, v[194:195]
	s_mov_b32 m0, s75
	ds_read_b128 v[184:187], v242
	ds_read_b128 v[188:191], v242 offset:1024
	ds_read_b128 v[216:219], v242 offset:2048
	ds_read_b128 v[220:223], v242 offset:3072
	global_load_lds_dwordx4 v[212:213], off
	v_lshl_add_u64 v[224:225], s[42:43], 0, v[198:199]
	s_add_i32 m0, s75, 0x2000
	s_nop 0
	global_load_lds_dwordx4 v[224:225], off
	s_barrier
	s_waitcnt lgkmcnt(0)
	s_setprio 1
	v_mfma_f32_16x16x32_bf16 v[116:119], v[184:187], v[152:155], v[116:119]
	v_mfma_f32_16x16x32_bf16 v[112:115], v[216:219], v[152:155], v[112:115]
	v_mfma_f32_16x16x32_bf16 v[100:103], v[184:187], v[160:163], v[100:103]
	v_mfma_f32_16x16x32_bf16 v[96:99], v[216:219], v[160:163], v[96:99]
	v_mfma_f32_16x16x32_bf16 v[84:87], v[184:187], v[168:171], v[84:87]
	v_mfma_f32_16x16x32_bf16 v[80:83], v[216:219], v[168:171], v[80:83]
	v_mfma_f32_16x16x32_bf16 v[68:71], v[184:187], v[176:179], v[68:71]
	v_mfma_f32_16x16x32_bf16 v[64:67], v[216:219], v[176:179], v[64:67]
	v_mfma_f32_16x16x32_bf16 v[116:119], v[188:191], v[156:159], v[116:119]
	v_mfma_f32_16x16x32_bf16 v[112:115], v[220:223], v[156:159], v[112:115]
	v_mfma_f32_16x16x32_bf16 v[100:103], v[188:191], v[164:167], v[100:103]
	v_mfma_f32_16x16x32_bf16 v[96:99], v[220:223], v[164:167], v[96:99]
	v_mfma_f32_16x16x32_bf16 v[84:87], v[188:191], v[172:175], v[84:87]
	v_mfma_f32_16x16x32_bf16 v[80:83], v[220:223], v[172:175], v[80:83]
	v_mfma_f32_16x16x32_bf16 v[68:71], v[188:191], v[180:183], v[68:71]
	v_mfma_f32_16x16x32_bf16 v[64:67], v[220:223], v[180:183], v[64:67]
	s_setprio 0
	s_mov_b32 m0, s48
	v_lshl_add_u64 v[226:227], s[44:45], 0, v[192:193]
	s_barrier
; #define PG8_STAGE(bufoff, gbase, voff) do { _Pragma("unroll") for (int _i = 0; _i < 2; ++_i) \
;         __builtin_amdgcn_global_load_lds((const unsigned*)((const char*)(gbase) + (voff)[_i]), (LAS unsigned*)(lds + (bufoff) + ldsw + _i * 8192), 16, 0, 0); } while (0)
; #define PG8_LDA(dst, b, h) do { _Pragma("unroll") for (int m = 0; m < 4; ++m) _Pragma("unroll") for (int k = 0; k < 2; ++k) dst[m][k] = *(const LAS bf16x8*)(lds + PG8_SA(b, h) + aoff + m * 2048 + k * 1024); } while (0)
; #define PG8_LDB(dst, b, h) do { _Pragma("unroll") for (int n = 0; n < 2; ++n) _Pragma("unroll") for (int k = 0; k < 2; ++k) dst[n][k] = *(const LAS bf16x8*)(lds + PG8_SB(b, h) + boff + n * 2048 + k * 1024); } while (0)
; #define PG8_MMA(ai, bj, At, Bt) do { __builtin_amdgcn_s_setprio(1); _Pragma("unroll") for (int m = 0; m < 4; ++m) _Pragma("unroll") for (int n = 0; n < 2; ++n) _Pragma("unroll") for (int k = 0; k < 2; ++k) \
;         acc[ai][bj][m][n] = __builtin_amdgcn_mfma_f32_16x16x32_bf16(Bt[n][k], At[m][k], acc[ai][bj][m][n], 0, 0, 0); __builtin_amdgcn_s_setprio(0); } while (0)
; #define PG8_WAIT_V(n) asm volatile("s_waitcnt vmcnt(" #n ")" ::: "memory")
; #define PG8_WAIT_L(n) asm volatile("s_waitcnt lgkmcnt(" #n ")" ::: "memory")
; #define PG8_BAR __builtin_amdgcn_s_barrier()
; #define PG8_SCHED __builtin_amdgcn_sched_barrier(0)
; template <class Epi>
; __device__ __forceinline__ void gemm_phase(LAS unsigned char* lds, const GSched& S, const int K, const int lda, const int ldb, const Epi& E) {
;     ...
;             PG8_LDA(At, 0, 1); PG8_STAGE(PG8_SA(0, 0), a2, voffA);
;             PG8_BAR; PG8_WAIT_L(0); PG8_MMA(1, 0, At, B0); PG8_BAR; PG8_SCHED;
;             PG8_STAGE(PG8_SB(0, 1), b2 + hstepB, voffB);
;             PG8_WAIT_V(6); PG8_BAR; if constexpr (!Epi::NARROW) PG8_MMA(1, 1, At, B1); PG8_BAR;
;             PG8_LDB(B0, 1, 0); PG8_SCHED; PG8_LDA(At, 1, 0); PG8_STAGE(PG8_SA(0, 1), a2 + hstepA, voffA);
;             PG8_WAIT_L(8); PG8_BAR; PG8_WAIT_L(0); PG8_MMA(0, 0, At, B0); PG8_BAR; PG8_SCHED;
;             if constexpr (!Epi::NARROW) PG8_LDB(B1, 1, 1); PG8_STAGE(PG8_SB(1, 0), b3, voffB);
	ds_read_b128 v[152:155], v240 offset:16384
	ds_read_b128 v[156:159], v240 offset:17408
	ds_read_b128 v[160:163], v240 offset:18432
	ds_read_b128 v[164:167], v240 offset:19456
	ds_read_b128 v[168:171], v240 offset:20480
	ds_read_b128 v[172:175], v240 offset:21504
	ds_read_b128 v[176:179], v240 offset:22528
	ds_read_b128 v[180:183], v240 offset:23552
	global_load_lds_dwordx4 v[226:227], off
	v_lshl_add_u64 v[228:229], s[44:45], 0, v[196:197]
	s_mov_b32 m0, s49
	s_nop 0
	global_load_lds_dwordx4 v[228:229], off
	s_barrier
	s_waitcnt lgkmcnt(0)
	s_setprio 1
	v_mfma_f32_16x16x32_bf16 v[60:63], v[132:135], v[152:155], v[60:63]
	v_mfma_f32_16x16x32_bf16 v[56:59], v[140:143], v[152:155], v[56:59]
	v_mfma_f32_16x16x32_bf16 v[44:47], v[132:135], v[160:163], v[44:47]
	v_mfma_f32_16x16x32_bf16 v[40:43], v[140:143], v[160:163], v[40:43]
	v_mfma_f32_16x16x32_bf16 v[28:31], v[132:135], v[168:171], v[28:31]
	v_mfma_f32_16x16x32_bf16 v[24:27], v[140:143], v[168:171], v[24:27]
	v_mfma_f32_16x16x32_bf16 v[12:15], v[132:135], v[176:179], v[12:15]
	v_mfma_f32_16x16x32_bf16 v[8:11], v[140:143], v[176:179], v[8:11]
	v_mfma_f32_16x16x32_bf16 v[60:63], v[136:139], v[156:159], v[60:63]
	v_mfma_f32_16x16x32_bf16 v[56:59], v[144:147], v[156:159], v[56:59]
	v_mfma_f32_16x16x32_bf16 v[44:47], v[136:139], v[164:167], v[44:47]
	v_mfma_f32_16x16x32_bf16 v[40:43], v[144:147], v[164:167], v[40:43]
	v_mfma_f32_16x16x32_bf16 v[28:31], v[136:139], v[172:175], v[28:31]
	v_mfma_f32_16x16x32_bf16 v[24:27], v[144:147], v[172:175], v[24:27]
	v_mfma_f32_16x16x32_bf16 v[12:15], v[136:139], v[180:183], v[12:15]
	v_mfma_f32_16x16x32_bf16 v[8:11], v[144:147], v[180:183], v[8:11]
	s_setprio 0
	s_barrier
	s_add_u32 s76, s42, 0x90000
	s_addc_u32 s77, s43, 0
	s_add_i32 s75, s64, s47
	v_lshl_add_u64 v[130:131], s[76:77], 0, v[194:195]
	s_mov_b32 m0, s75
	s_nop 0
	global_load_lds_dwordx4 v[130:131], off
	v_lshl_add_u64 v[130:131], s[76:77], 0, v[198:199]
	s_add_i32 m0, s75, 0x2000
	s_nop 0
	global_load_lds_dwordx4 v[130:131], off
	s_waitcnt vmcnt(6)
	s_barrier
	s_setprio 1
	v_mfma_f32_16x16x32_bf16 v[52:55], v[184:187], v[152:155], v[52:55]
	v_mfma_f32_16x16x32_bf16 v[48:51], v[216:219], v[152:155], v[48:51]
	v_mfma_f32_16x16x32_bf16 v[36:39], v[184:187], v[160:163], v[36:39]
	v_mfma_f32_16x16x32_bf16 v[32:35], v[216:219], v[160:163], v[32:35]
	v_mfma_f32_16x16x32_bf16 v[20:23], v[184:187], v[168:171], v[20:23]
	v_mfma_f32_16x16x32_bf16 v[16:19], v[216:219], v[168:171], v[16:19]
	v_mfma_f32_16x16x32_bf16 v[4:7], v[184:187], v[176:179], v[4:7]
	v_mfma_f32_16x16x32_bf16 v[0:3], v[216:219], v[176:179], v[0:3]
	v_mfma_f32_16x16x32_bf16 v[52:55], v[188:191], v[156:159], v[52:55]
	v_mfma_f32_16x16x32_bf16 v[48:51], v[220:223], v[156:159], v[48:51]
	v_mfma_f32_16x16x32_bf16 v[36:39], v[188:191], v[164:167], v[36:39]
	v_mfma_f32_16x16x32_bf16 v[32:35], v[220:223], v[164:167], v[32:35]
	v_mfma_f32_16x16x32_bf16 v[20:23], v[188:191], v[172:175], v[20:23]
	v_mfma_f32_16x16x32_bf16 v[16:19], v[220:223], v[172:175], v[16:19]
	v_mfma_f32_16x16x32_bf16 v[4:7], v[188:191], v[180:183], v[4:7]
	v_mfma_f32_16x16x32_bf16 v[0:3], v[220:223], v[180:183], v[0:3]
	s_setprio 0
	s_add_i32 s75, 0, 0x18000
	v_add_u32_e32 v130, s75, v238
	s_barrier
	ds_read_b128 v[132:135], v130
	ds_read_b128 v[136:139], v130 offset:1024
	ds_read_b128 v[140:143], v130 offset:2048
	ds_read_b128 v[144:147], v130 offset:3072
	s_add_u32 s44, s44, 0x94000
	s_addc_u32 s45, s45, 0
	s_mov_b32 m0, s50
	v_lshl_add_u64 v[130:131], s[44:45], 0, v[192:193]
	ds_read_b128 v[152:155], v240 offset:32768
	ds_read_b128 v[156:159], v240 offset:33792
	ds_read_b128 v[160:163], v240 offset:34816
	ds_read_b128 v[164:167], v240 offset:35840
	ds_read_b128 v[168:171], v240 offset:36864
	ds_read_b128 v[172:175], v240 offset:37888
	ds_read_b128 v[176:179], v240 offset:38912
	ds_read_b128 v[180:183], v240 offset:39936
	global_load_lds_dwordx4 v[130:131], off
	v_lshl_add_u64 v[130:131], s[44:45], 0, v[196:197]
	s_mov_b32 m0, s51
	s_nop 0
	global_load_lds_dwordx4 v[130:131], off
	s_waitcnt lgkmcnt(8)
	s_barrier
	s_waitcnt lgkmcnt(0)
	s_setprio 1
	s_waitcnt lgkmcnt(0)
	v_mfma_f32_16x16x32_bf16 v[148:151], v[132:135], v[152:155], v[148:151]
	v_mfma_f32_16x16x32_bf16 v[126:129], v[140:143], v[152:155], v[126:129]
	v_mfma_f32_16x16x32_bf16 v[108:111], v[132:135], v[160:163], v[108:111]
	v_mfma_f32_16x16x32_bf16 v[104:107], v[140:143], v[160:163], v[104:107]
	v_mfma_f32_16x16x32_bf16 v[92:95], v[132:135], v[168:171], v[92:95]
	v_mfma_f32_16x16x32_bf16 v[88:91], v[140:143], v[168:171], v[88:91]
	v_mfma_f32_16x16x32_bf16 v[76:79], v[132:135], v[176:179], v[76:79]
	v_mfma_f32_16x16x32_bf16 v[72:75], v[140:143], v[176:179], v[72:75]
	v_mfma_f32_16x16x32_bf16 v[148:151], v[136:139], v[156:159], v[148:151]
	v_mfma_f32_16x16x32_bf16 v[128:131], v[144:147], v[156:159], v[126:129]
	v_mfma_f32_16x16x32_bf16 v[108:111], v[136:139], v[164:167], v[108:111]
	v_mfma_f32_16x16x32_bf16 v[104:107], v[144:147], v[164:167], v[104:107]
	v_mfma_f32_16x16x32_bf16 v[92:95], v[136:139], v[172:175], v[92:95]
	v_mfma_f32_16x16x32_bf16 v[88:91], v[144:147], v[172:175], v[88:91]
	v_mfma_f32_16x16x32_bf16 v[76:79], v[136:139], v[180:183], v[76:79]
	v_mfma_f32_16x16x32_bf16 v[72:75], v[144:147], v[180:183], v[72:75]
	s_setprio 0
	s_barrier
	s_add_i32 s44, 0, 0x1c000
	v_add_u32_e32 v126, s44, v238
	s_add_i32 s45, s75, s47
	ds_read_b128 v[184:187], v126
	ds_read_b128 v[188:191], v126 offset:1024
	ds_read_b128 v[216:219], v126 offset:2048
	ds_read_b128 v[220:223], v126 offset:3072
	v_lshl_add_u64 v[126:127], v[212:213], 0, s[34:35]
	s_mov_b32 m0, s45
	s_nop 0
	global_load_lds_dwordx4 v[126:127], off
	v_lshl_add_u64 v[126:127], v[224:225], 0, s[34:35]
	s_add_i32 m0, s45, 0x2000
	s_nop 0
	global_load_lds_dwordx4 v[126:127], off
	s_barrier
; #define PG8_STAGE(bufoff, gbase, voff) do { _Pragma("unroll") for (int _i = 0; _i < 2; ++_i) \
;         __builtin_amdgcn_global_load_lds((const unsigned*)((const char*)(gbase) + (voff)[_i]), (LAS unsigned*)(lds + (bufoff) + ldsw + _i * 8192), 16, 0, 0); } while (0)
; #define PG8_LDA(dst, b, h) do { _Pragma("unroll") for (int m = 0; m < 4; ++m) _Pragma("unroll") for (int k = 0; k < 2; ++k) dst[m][k] = *(const LAS bf16x8*)(lds + PG8_SA(b, h) + aoff + m * 2048 + k * 1024); } while (0)
; #define PG8_MMA(ai, bj, At, Bt) do { __builtin_amdgcn_s_setprio(1); _Pragma("unroll") for (int m = 0; m < 4; ++m) _Pragma("unroll") for (int n = 0; n < 2; ++n) _Pragma("unroll") for (int k = 0; k < 2; ++k) \
;         acc[ai][bj][m][n] = __builtin_amdgcn_mfma_f32_16x16x32_bf16(Bt[n][k], At[m][k], acc[ai][bj][m][n], 0, 0, 0); __builtin_amdgcn_s_setprio(0); } while (0)
; #define PG8_WAIT_V(n) asm volatile("s_waitcnt vmcnt(" #n ")" ::: "memory")
; #define PG8_WAIT_L(n) asm volatile("s_waitcnt lgkmcnt(" #n ")" ::: "memory")
; #define PG8_BAR __builtin_amdgcn_s_barrier()
; #define PG8_SCHED __builtin_amdgcn_sched_barrier(0)
; template <class Epi>
; __device__ __forceinline__ void gemm_phase(LAS unsigned char* lds, const GSched& S, const int K, const int lda, const int ldb, const Epi& E) {
;     ...
;             PG8_BAR; PG8_WAIT_L(0); if constexpr (!Epi::NARROW) PG8_MMA(0, 1, At, B1); PG8_BAR;
;             PG8_LDA(At, 1, 1); PG8_STAGE(PG8_SA(1, 0), a3, voffA);
;             PG8_BAR; PG8_WAIT_L(0); PG8_MMA(1, 0, At, B0); PG8_BAR; PG8_SCHED;
;             PG8_STAGE(PG8_SB(1, 1), b3 + hstepB, voffB);
;             PG8_WAIT_V(6); PG8_BAR; if constexpr (!Epi::NARROW) PG8_MMA(1, 1, At, B1); PG8_BAR;
;             if constexpr (Epi::HAS_MID) { if (t + 2 == E.mid_t) { PG8_SCHED; E.mid(acc, cur, wr, wc, fr, fq); PG8_SCHED; } }
	s_waitcnt lgkmcnt(0)
	s_setprio 1
	v_mfma_f32_16x16x32_bf16 v[116:119], v[184:187], v[152:155], v[116:119]
	v_mfma_f32_16x16x32_bf16 v[112:115], v[216:219], v[152:155], v[112:115]
	v_mfma_f32_16x16x32_bf16 v[100:103], v[184:187], v[160:163], v[100:103]
	v_mfma_f32_16x16x32_bf16 v[96:99], v[216:219], v[160:163], v[96:99]
	v_mfma_f32_16x16x32_bf16 v[84:87], v[184:187], v[168:171], v[84:87]
	v_mfma_f32_16x16x32_bf16 v[80:83], v[216:219], v[168:171], v[80:83]
	v_mfma_f32_16x16x32_bf16 v[68:71], v[184:187], v[176:179], v[68:71]
	v_mfma_f32_16x16x32_bf16 v[64:67], v[216:219], v[176:179], v[64:67]
	v_mfma_f32_16x16x32_bf16 v[116:119], v[188:191], v[156:159], v[116:119]
	v_mfma_f32_16x16x32_bf16 v[112:115], v[220:223], v[156:159], v[112:115]
	v_mfma_f32_16x16x32_bf16 v[100:103], v[188:191], v[164:167], v[100:103]
	v_mfma_f32_16x16x32_bf16 v[96:99], v[220:223], v[164:167], v[96:99]
	v_mfma_f32_16x16x32_bf16 v[84:87], v[188:191], v[172:175], v[84:87]
	v_mfma_f32_16x16x32_bf16 v[80:83], v[220:223], v[172:175], v[80:83]
	v_mfma_f32_16x16x32_bf16 v[68:71], v[188:191], v[180:183], v[68:71]
	v_mfma_f32_16x16x32_bf16 v[64:67], v[220:223], v[180:183], v[64:67]
	s_setprio 0
	s_mov_b32 m0, s58
	v_lshl_add_u64 v[126:127], v[226:227], 0, s[34:35]
	s_barrier
	ds_read_b128 v[152:155], v240 offset:49152
	ds_read_b128 v[156:159], v240 offset:50176
	ds_read_b128 v[160:163], v240 offset:51200
	ds_read_b128 v[164:167], v240 offset:52224
	ds_read_b128 v[168:171], v240 offset:53248
	ds_read_b128 v[172:175], v240 offset:54272
	ds_read_b128 v[176:179], v240 offset:55296
	ds_read_b128 v[180:183], v240 offset:56320
	global_load_lds_dwordx4 v[126:127], off
	v_lshl_add_u64 v[126:127], v[228:229], 0, s[34:35]
	s_mov_b32 m0, s59
	s_nop 0
	global_load_lds_dwordx4 v[126:127], off
	s_barrier
	s_waitcnt lgkmcnt(0)
	s_setprio 1
	v_mfma_f32_16x16x32_bf16 v[60:63], v[132:135], v[152:155], v[60:63]
	v_mfma_f32_16x16x32_bf16 v[56:59], v[140:143], v[152:155], v[56:59]
	v_mfma_f32_16x16x32_bf16 v[44:47], v[132:135], v[160:163], v[44:47]
	v_mfma_f32_16x16x32_bf16 v[40:43], v[140:143], v[160:163], v[40:43]
	v_mfma_f32_16x16x32_bf16 v[28:31], v[132:135], v[168:171], v[28:31]
	v_mfma_f32_16x16x32_bf16 v[24:27], v[140:143], v[168:171], v[24:27]
	v_mfma_f32_16x16x32_bf16 v[12:15], v[132:135], v[176:179], v[12:15]
	v_mfma_f32_16x16x32_bf16 v[8:11], v[140:143], v[176:179], v[8:11]
	v_mfma_f32_16x16x32_bf16 v[60:63], v[136:139], v[156:159], v[60:63]
	v_mfma_f32_16x16x32_bf16 v[56:59], v[144:147], v[156:159], v[56:59]
	v_mfma_f32_16x16x32_bf16 v[44:47], v[136:139], v[164:167], v[44:47]
	v_mfma_f32_16x16x32_bf16 v[40:43], v[144:147], v[164:167], v[40:43]
	v_mfma_f32_16x16x32_bf16 v[28:31], v[136:139], v[172:175], v[28:31]
	v_mfma_f32_16x16x32_bf16 v[24:27], v[144:147], v[172:175], v[24:27]
	v_mfma_f32_16x16x32_bf16 v[12:15], v[136:139], v[180:183], v[12:15]
	v_mfma_f32_16x16x32_bf16 v[8:11], v[144:147], v[180:183], v[8:11]
	s_setprio 0
	s_barrier
	s_add_u32 s42, s42, 0x90080
	s_addc_u32 s43, s43, 0
	s_add_i32 s44, s44, s47
	v_lshl_add_u64 v[126:127], s[42:43], 0, v[194:195]
	s_mov_b32 m0, s44
	s_nop 0
	global_load_lds_dwordx4 v[126:127], off
	v_lshl_add_u64 v[126:127], s[42:43], 0, v[198:199]
	s_add_i32 m0, s44, 0x2000
	s_nop 0
	global_load_lds_dwordx4 v[126:127], off
	s_waitcnt vmcnt(6)
	s_barrier
	s_setprio 1
	v_mfma_f32_16x16x32_bf16 v[52:55], v[184:187], v[152:155], v[52:55]
	v_mfma_f32_16x16x32_bf16 v[48:51], v[216:219], v[152:155], v[48:51]
	v_mfma_f32_16x16x32_bf16 v[36:39], v[184:187], v[160:163], v[36:39]
	v_mfma_f32_16x16x32_bf16 v[32:35], v[216:219], v[160:163], v[32:35]
	v_mfma_f32_16x16x32_bf16 v[20:23], v[184:187], v[168:171], v[20:23]
	v_mfma_f32_16x16x32_bf16 v[16:19], v[216:219], v[168:171], v[16:19]
	v_mfma_f32_16x16x32_bf16 v[4:7], v[184:187], v[176:179], v[4:7]
	v_mfma_f32_16x16x32_bf16 v[0:3], v[216:219], v[176:179], v[0:3]
	v_mfma_f32_16x16x32_bf16 v[52:55], v[188:191], v[156:159], v[52:55]
	v_mfma_f32_16x16x32_bf16 v[48:51], v[220:223], v[156:159], v[48:51]
	v_mfma_f32_16x16x32_bf16 v[36:39], v[188:191], v[164:167], v[36:39]
	v_mfma_f32_16x16x32_bf16 v[32:35], v[220:223], v[164:167], v[32:35]
	v_mfma_f32_16x16x32_bf16 v[20:23], v[188:191], v[172:175], v[20:23]
	v_mfma_f32_16x16x32_bf16 v[16:19], v[220:223], v[172:175], v[16:19]
	v_mfma_f32_16x16x32_bf16 v[4:7], v[188:191], v[180:183], v[4:7]
	v_mfma_f32_16x16x32_bf16 v[0:3], v[220:223], v[180:183], v[0:3]
	s_setprio 0
	s_add_i32 s42, s39, 2
	s_cmp_lg_u32 s42, 4
	s_barrier
	s_cbranch_scc1 .LBB0_1204
; __device__ __forceinline__ u32x4 pack8(const f32x4 a, const f32x4 b) { u32x4 w; w.x = cvt_pk_bf16(a[0], a[1]); w.y = cvt_pk_bf16(a[2], a[3]); w.z = cvt_pk_bf16(b[0], b[1]); w.w = cvt_pk_bf16(b[2], b[3]); return w; }
;     __device__ __forceinline__ void mid(Acc& acc, const Unit& u, int wr, int wc, int fr, int fq) const {
;         int row0 = u.pm * BM + wr * 64 + fr; asm volatile("" : "+v"(row0));
;         bf16_t* eb = etmp + (size_t)row0 * 2048 + u.pn * BM + wc * 32 + 8 * fq;
; #pragma unroll
;         for (int ai = 0; ai < 2; ++ai)
; #pragma unroll
;             for (int m = 0; m < 4; ++m) {
; #pragma unroll
;                 for (int bj = 0; bj < 2; ++bj) { *(u32x4*)(eb + (size_t)(ai * HALF + m * 16) * 2048 + bj * HALF) = pack8(acc[ai][bj][m][0], acc[ai][bj][m][1]);
;                     acc[ai][bj][m][0] = (f32x4){0.f, 0.f, 0.f, 0.f}; acc[ai][bj][m][1] = (f32x4){0.f, 0.f, 0.f, 0.f}; } }
;     }
	v_mov_b32_e32 v126, v214
	v_cvt_pk_bf16_f32 v108, v108, v109
	v_ashrrev_i32_e32 v127, 31, v126
	v_lshlrev_b64 v[126:127], 12, v[126:127]
	v_lshl_add_u64 v[132:133], v[120:121], 0, v[126:127]
	v_cvt_pk_bf16_f32 v109, v110, v111
	v_cvt_pk_bf16_f32 v110, v104, v105
	v_add_co_u32_e32 v104, vcc, s52, v132
	v_cvt_pk_bf16_f32 v92, v92, v93
	s_nop 0
	v_addc_co_u32_e32 v105, vcc, 0, v133, vcc
	v_cvt_pk_bf16_f32 v93, v94, v95
	v_cvt_pk_bf16_f32 v94, v88, v89
	v_add_co_u32_e32 v88, vcc, s65, v132
	v_cvt_pk_bf16_f32 v76, v76, v77
	s_nop 0
	v_addc_co_u32_e32 v89, vcc, 0, v133, vcc
	v_cvt_pk_bf16_f32 v77, v78, v79
	v_cvt_pk_bf16_f32 v78, v72, v73
	v_add_co_u32_e32 v72, vcc, s66, v132
	v_cvt_pk_bf16_f32 v60, v60, v61
	s_nop 0
	v_addc_co_u32_e32 v73, vcc, 0, v133, vcc
	v_cvt_pk_bf16_f32 v61, v62, v63
	v_cvt_pk_bf16_f32 v62, v56, v57
	v_add_co_u32_e32 v56, vcc, s67, v132
	v_cvt_pk_bf16_f32 v44, v44, v45
	s_nop 0
	v_addc_co_u32_e32 v57, vcc, 0, v133, vcc
	v_cvt_pk_bf16_f32 v45, v46, v47
	v_cvt_pk_bf16_f32 v46, v40, v41
	v_add_co_u32_e32 v40, vcc, s68, v132
	v_cvt_pk_bf16_f32 v28, v28, v29
	s_nop 0
	v_addc_co_u32_e32 v41, vcc, 0, v133, vcc
	v_cvt_pk_bf16_f32 v29, v30, v31
	v_cvt_pk_bf16_f32 v30, v24, v25
	v_add_co_u32_e32 v24, vcc, s69, v132
	v_cvt_pk_bf16_f32 v12, v12, v13
	s_nop 0
	v_addc_co_u32_e32 v25, vcc, 0, v133, vcc
	v_cvt_pk_bf16_f32 v13, v14, v15
	v_cvt_pk_bf16_f32 v14, v8, v9
	v_add_co_u32_e32 v8, vcc, s70, v132
	v_cvt_pk_bf16_f32 v126, v148, v149
	v_cvt_pk_bf16_f32 v127, v150, v151
	v_cvt_pk_bf16_f32 v128, v128, v129
	v_cvt_pk_bf16_f32 v129, v130, v131
	v_cvt_pk_bf16_f32 v116, v116, v117
	v_cvt_pk_bf16_f32 v117, v118, v119
	v_cvt_pk_bf16_f32 v118, v112, v113
	v_cvt_pk_bf16_f32 v119, v114, v115
	v_cvt_pk_bf16_f32 v111, v106, v107
	v_cvt_pk_bf16_f32 v100, v100, v101
	v_cvt_pk_bf16_f32 v101, v102, v103
	v_cvt_pk_bf16_f32 v102, v96, v97
	v_cvt_pk_bf16_f32 v103, v98, v99
	v_cvt_pk_bf16_f32 v95, v90, v91
	v_cvt_pk_bf16_f32 v84, v84, v85
	v_cvt_pk_bf16_f32 v85, v86, v87
	v_cvt_pk_bf16_f32 v86, v80, v81
	v_cvt_pk_bf16_f32 v87, v82, v83
	v_cvt_pk_bf16_f32 v79, v74, v75
	v_cvt_pk_bf16_f32 v68, v68, v69
	v_cvt_pk_bf16_f32 v69, v70, v71
	v_cvt_pk_bf16_f32 v70, v64, v65
	v_cvt_pk_bf16_f32 v71, v66, v67
	v_cvt_pk_bf16_f32 v63, v58, v59
	v_cvt_pk_bf16_f32 v52, v52, v53
	v_cvt_pk_bf16_f32 v53, v54, v55
	v_cvt_pk_bf16_f32 v54, v48, v49
	v_cvt_pk_bf16_f32 v55, v50, v51
	v_cvt_pk_bf16_f32 v47, v42, v43
	v_cvt_pk_bf16_f32 v36, v36, v37
	v_cvt_pk_bf16_f32 v37, v38, v39
	v_cvt_pk_bf16_f32 v38, v32, v33
	v_cvt_pk_bf16_f32 v39, v34, v35
	v_cvt_pk_bf16_f32 v31, v26, v27
	v_cvt_pk_bf16_f32 v20, v20, v21
	v_cvt_pk_bf16_f32 v21, v22, v23
	v_cvt_pk_bf16_f32 v22, v16, v17
	v_cvt_pk_bf16_f32 v23, v18, v19
	v_cvt_pk_bf16_f32 v15, v10, v11
	v_addc_co_u32_e32 v9, vcc, 0, v133, vcc
	v_cvt_pk_bf16_f32 v4, v4, v5
	v_cvt_pk_bf16_f32 v5, v6, v7
	v_cvt_pk_bf16_f32 v6, v0, v1
	v_cvt_pk_bf16_f32 v7, v2, v3
	global_store_dwordx4 v[132:133], v[126:129], off
	global_store_dwordx4 v[132:133], v[116:119], off offset:256
	global_store_dwordx4 v[104:105], v[108:111], off
	global_store_dwordx4 v[104:105], v[100:103], off offset:256
	global_store_dwordx4 v[88:89], v[92:95], off
	global_store_dwordx4 v[88:89], v[84:87], off offset:256
	global_store_dwordx4 v[72:73], v[76:79], off
	global_store_dwordx4 v[72:73], v[68:71], off offset:256
	global_store_dwordx4 v[56:57], v[60:63], off
	global_store_dwordx4 v[56:57], v[52:55], off offset:256
	global_store_dwordx4 v[40:41], v[44:47], off
	global_store_dwordx4 v[40:41], v[36:39], off offset:256
	global_store_dwordx4 v[24:25], v[28:31], off
	global_store_dwordx4 v[24:25], v[20:23], off offset:256
	global_store_dwordx4 v[8:9], v[12:15], off
	global_store_dwordx4 v[8:9], v[4:7], off offset:256
	v_mov_b32_e32 v0, 0
	v_mov_b64_e32 v[0:1], 0
	v_mov_b64_e32 v[2:3], 0
	v_mov_b64_e32 v[4:5], 0
	v_mov_b64_e32 v[6:7], 0
	v_mov_b64_e32 v[8:9], 0
	v_mov_b64_e32 v[10:11], 0
	v_mov_b64_e32 v[12:13], 0
	v_mov_b64_e32 v[14:15], 0
	v_mov_b64_e32 v[16:17], 0
	v_mov_b64_e32 v[18:19], 0
	v_mov_b64_e32 v[20:21], 0
	v_mov_b64_e32 v[22:23], 0
	v_mov_b64_e32 v[24:25], 0
	v_mov_b64_e32 v[26:27], 0
	v_mov_b64_e32 v[28:29], 0
	v_mov_b64_e32 v[30:31], 0
	v_mov_b64_e32 v[32:33], 0
	v_mov_b64_e32 v[34:35], 0
	v_mov_b64_e32 v[36:37], 0
	v_mov_b64_e32 v[38:39], 0
	v_mov_b64_e32 v[40:41], 0
	v_mov_b64_e32 v[42:43], 0
	v_mov_b64_e32 v[44:45], 0
	v_mov_b64_e32 v[46:47], 0
	v_mov_b64_e32 v[48:49], 0
	v_mov_b64_e32 v[50:51], 0
	v_mov_b64_e32 v[52:53], 0
	v_mov_b64_e32 v[54:55], 0
	v_mov_b64_e32 v[56:57], 0
	v_mov_b64_e32 v[58:59], 0
	v_mov_b64_e32 v[60:61], 0
	v_mov_b64_e32 v[62:63], 0
	v_mov_b64_e32 v[64:65], 0
	v_mov_b64_e32 v[66:67], 0
	v_mov_b64_e32 v[68:69], 0
	v_mov_b64_e32 v[70:71], 0
	v_mov_b64_e32 v[72:73], 0
	v_mov_b64_e32 v[74:75], 0
	v_mov_b64_e32 v[76:77], 0
	v_mov_b64_e32 v[78:79], 0
	v_mov_b64_e32 v[80:81], 0
	v_mov_b64_e32 v[82:83], 0
	v_mov_b64_e32 v[84:85], 0
	v_mov_b64_e32 v[86:87], 0
	v_mov_b64_e32 v[88:89], 0
	v_mov_b64_e32 v[90:91], 0
	v_mov_b64_e32 v[92:93], 0
	v_mov_b64_e32 v[94:95], 0
	v_mov_b64_e32 v[96:97], 0
	v_mov_b64_e32 v[98:99], 0
	v_mov_b64_e32 v[100:101], 0
	v_mov_b64_e32 v[102:103], 0
	v_mov_b64_e32 v[104:105], 0
	v_mov_b64_e32 v[106:107], 0
	v_mov_b64_e32 v[108:109], 0
	v_mov_b64_e32 v[110:111], 0
	v_mov_b64_e32 v[112:113], 0
	v_mov_b64_e32 v[114:115], 0
	v_mov_b64_e32 v[116:117], 0
	v_mov_b64_e32 v[118:119], 0
	v_mov_b64_e32 v[128:129], 0
	v_mov_b64_e32 v[130:131], 0
	v_mov_b64_e32 v[148:149], 0
	v_mov_b64_e32 v[150:151], 0
	s_nop 0
